# E score GEMM K loop: all LDS fragment reads hoisted, read-phase barrier, next K-step LDS-DMA issued before 24 of the 32 MFMAs so its latency overlaps them
# speedup vs baseline: 1.0029x; 1.0029x over previous
; __device__ __forceinline__ int otid() { int t = threadIdx.x; asm volatile("" : "+v"(t)); return t; }
; template <int MI, bool SWAP, bool F8 = false>
; __device__ __forceinline__ void gemm_core(const bf16_t* __restrict__ A, int lda, const bf16_t* __restrict__ B, int ldb,
;                                           int K, char* smem, f32x4 (&acc)[MI][4]) {
;   const int tid = otid(), lane = tid & 63, w = tid >> 6, wm = w >> 1, wn = w & 1;
;   const int lr = tid >> 3, lc = tid & 7;
;   const int li = lane & 15, g = lane >> 4;
;   u32x4 ra[MI], rb[4];
;   const bf16_t* ap = A + (size_t)lr * lda + lc * 8;
;   const bf16_t* bp = B + (size_t)lr * ldb + lc * 8;
; #pragma unroll
;   for (int i = 0; i < MI; ++i)
; #pragma unroll
;     for (int j = 0; j < 4; ++j) acc[i][j] = (f32x4){0.f, 0.f, 0.f, 0.f};
;   const int nk = K >> 6;
; #pragma unroll
;   for (int i = 0; i < MI; ++i) ra[i] = *(const u32x4*)(ap + (size_t)(32 * i) * lda);
; #pragma unroll
;   for (int i = 0; i < 4; ++i) rb[i] = *(const u32x4*)(bp + (size_t)(32 * i) * ldb);
;   const int woff = lr * 128 + ((lc ^ (lr & 7)) << 4);
;   const int xrow = (wm * 16 * MI + li) * 128;
;   const int wrow = 32768 + (wn * 32 + li) * 128;
;   for (int kt = 0; kt < nk; ++kt) {
; __global__ void __launch_bounds__(256, 2) fwd_kernel(P p) {
;     ...
;       for (int it = blockIdx.x; it < 64 * 16; it += G) {
;         const int tm = (it & 7) * 8 + ((it >> 3) >> 4), tn = (it >> 3) & 15;
;         gemm_tile_bf16<8, true>((const bf16_t*)(ws + OFF_AO + (32ull << 20)) + (size_t)tm * 256 * 512, 512,
;                        (const bf16_t*)(ws + OFF_WPQ) + ((size_t)layer * 2048 + tn * 128) * 512, 512, 512,
;                        SCB + (size_t)tm * 256 * 2048 + tn * 128, 2048, smem);
.LBB0_943:
	s_lshl_b32 s6, s14, 10
	s_and_b32 s66, s6, 0x1e0000
	s_lshl_b32 s6, s18, 3
	s_and_b32 s6, s6, 56
	s_ashr_i32 s23, s18, 7
	s_add_i32 s6, s6, s23
	s_ashr_i32 s7, s6, 31
	s_waitcnt vmcnt(15)
	v_mov_b32_e32 v36, v208
	s_and_b32 s22, s15, 56
	s_lshl_b64 s[8:9], s[6:7], 18
	s_add_u32 s8, s10, s8
	v_ashrrev_i32_e32 v2, 3, v36
	v_ashrrev_i32_e32 v3, 31, v2
	s_addc_u32 s9, s11, s9
	v_lshlrev_b64 v[32:33], 10, v[2:3]
	v_lshlrev_b32_e32 v0, 4, v36
	v_lshl_add_u64 v[20:21], s[8:9], 0, v[32:33]
	v_and_b32_e32 v0, 0x70, v0
	v_lshl_add_u64 v[30:31], v[20:21], 0, v[0:1]
	s_mov_b32 s8, 0x8000
	v_add_co_u32_e32 v20, vcc, s8, v30
	s_lshl_b32 s19, s18, 4
	s_nop 0
	v_addc_co_u32_e32 v21, vcc, 0, v31, vcc
	v_lshrrev_b32_e32 v254, 3, v208
	v_and_b32_e32 v254, 7, v254
	v_xor_b32_e32 v252, v254, v208
	v_and_b32_e32 v252, 7, v252
	v_lshlrev_b32_e32 v252, 4, v252
	v_lshl_or_b32 v252, v254, 10, v252
	v_add_u32_e32 v253, 0x8000, v252
	v_lshrrev_b32_e32 v254, 6, v208
	s_nop 0
	v_readfirstlane_b32 s62, v254
	s_lshl_b32 s62, s62, 10
	v_readfirstlane_b32 s56, v30
	v_readfirstlane_b32 s57, v31
	v_add_co_u32_e32 v20, vcc, s93, v30
	s_and_b32 s19, s19, 0x780
	s_nop 0
	v_addc_co_u32_e32 v21, vcc, 0, v31, vcc
	s_mov_b32 s9, 0x18000
	s_lshl_b32 s20, s19, 10
	v_add_co_u32_e32 v22, vcc, s9, v30
	s_add_u32 s20, s16, s20
	s_nop 0
	v_addc_co_u32_e32 v23, vcc, 0, v31, vcc
	s_addc_u32 s21, s17, 0
	v_add_co_u32_e32 v20, vcc, s46, v30
	v_lshl_add_u64 v[28:29], s[20:21], 0, v[32:33]
	s_nop 0
	v_addc_co_u32_e32 v21, vcc, 0, v31, vcc
	s_mov_b32 s20, 0x28000
	v_add_co_u32_e32 v24, vcc, s20, v30
	s_mov_b32 s20, 0x38000
	s_nop 0
	v_addc_co_u32_e32 v25, vcc, 0, v31, vcc
	v_add_co_u32_e32 v34, vcc, s47, v30
	v_lshl_add_u64 v[28:29], v[28:29], 0, v[0:1]
	s_nop 0
	v_addc_co_u32_e32 v35, vcc, 0, v31, vcc
	v_add_co_u32_e32 v30, vcc, s20, v30
	s_nop 0
	v_addc_co_u32_e32 v31, vcc, 0, v31, vcc
	v_add_co_u32_e32 v30, vcc, s8, v28
	v_lshlrev_b32_e32 v0, 7, v2
	s_nop 0
	v_addc_co_u32_e32 v31, vcc, 0, v29, vcc
	s_nop 0
	v_readfirstlane_b32 s58, v28
	v_readfirstlane_b32 s59, v29
	v_add_co_u32_e32 v30, vcc, s93, v28
	v_xor_b32_e32 v2, v2, v36
	s_nop 0
	v_addc_co_u32_e32 v31, vcc, 0, v29, vcc
	v_add_co_u32_e32 v28, vcc, s9, v28
	v_lshlrev_b32_e32 v2, 4, v2
	s_nop 0
	v_addc_co_u32_e32 v29, vcc, 0, v29, vcc
	s_nop 0
	v_and_or_b32 v0, v2, s33, v0
	v_lshlrev_b32_e32 v2, 7, v36
	v_and_b32_e32 v3, 15, v36
	v_and_b32_e32 v213, 0xffffc780, v2
	v_lshrrev_b32_e32 v2, 1, v36
	v_lshrrev_b32_e32 v37, 4, v36
	v_and_or_b32 v2, v2, 32, v3
	v_and_b32_e32 v35, 7, v36
	s_add_i32 s8, s23, s22
	v_bfe_u32 v34, v36, 4, 2
	v_lshlrev_b32_e32 v215, 7, v2
	v_bitop3_b32 v2, v37, v35, 3 bitop3:0x6c
	s_ashr_i32 s9, s8, 31
	v_lshlrev_b32_e32 v218, 4, v2
	v_bitop3_b32 v2, v34, v35, 4 bitop3:0x36
	s_lshl_b64 s[8:9], s[8:9], 18
	v_lshlrev_b32_e32 v219, 4, v2
	v_lshl_add_u64 v[2:3], s[8:9], 0, v[32:33]
	v_lshlrev_b32_e32 v34, 4, v35
	v_lshl_add_u64 v[32:33], s[66:67], 0, v[32:33]
	v_or_b32_e32 v2, v2, v34
	v_or_b32_e32 v32, v32, v34
	v_mov_b32_e32 v52, 0
	v_lshl_add_u64 v[2:3], s[12:13], 0, v[2:3]
	v_lshl_add_u64 v[216:217], s[0:1], 0, v[32:33]
	s_mov_b64 s[8:9], 0
	v_mov_b32_e32 v53, v52
	v_mov_b32_e32 v54, v52
	v_mov_b32_e32 v55, v52
	s_waitcnt vmcnt(23)
	v_mov_b32_e32 v56, v52
	v_mov_b32_e32 v57, v52
	v_mov_b32_e32 v58, v52
	v_mov_b32_e32 v59, v52
	v_mov_b32_e32 v60, v52
	v_mov_b32_e32 v61, v52
	v_mov_b32_e32 v62, v52
	v_mov_b32_e32 v63, v52
	s_waitcnt vmcnt(22)
	v_mov_b32_e32 v64, v52
	v_mov_b32_e32 v65, v52
	v_mov_b32_e32 v66, v52
	v_mov_b32_e32 v67, v52
	v_mov_b32_e32 v68, v52
	v_mov_b32_e32 v69, v52
	v_mov_b32_e32 v70, v52
	v_mov_b32_e32 v71, v52
	v_mov_b32_e32 v72, v52
	v_mov_b32_e32 v73, v52
	v_mov_b32_e32 v74, v52
	v_mov_b32_e32 v75, v52
	v_mov_b32_e32 v76, v52
	v_mov_b32_e32 v77, v52
	v_mov_b32_e32 v78, v52
	v_mov_b32_e32 v79, v52
	v_mov_b32_e32 v80, v52
	v_mov_b32_e32 v81, v52
	v_mov_b32_e32 v82, v52
	v_mov_b32_e32 v83, v52
	s_waitcnt vmcnt(21)
	v_mov_b32_e32 v84, v52
	v_mov_b32_e32 v85, v52
	v_mov_b32_e32 v86, v52
	v_mov_b32_e32 v87, v52
	s_waitcnt vmcnt(20)
	v_mov_b32_e32 v88, v52
	v_mov_b32_e32 v89, v52
	v_mov_b32_e32 v90, v52
	v_mov_b32_e32 v91, v52
	v_mov_b32_e32 v92, v52
	v_mov_b32_e32 v93, v52
	v_mov_b32_e32 v94, v52
	v_mov_b32_e32 v95, v52
	v_mov_b32_e32 v96, v52
	v_mov_b32_e32 v97, v52
	v_mov_b32_e32 v98, v52
	v_mov_b32_e32 v99, v52
	v_mov_b32_e32 v100, v52
	v_mov_b32_e32 v101, v52
	v_mov_b32_e32 v102, v52
	v_mov_b32_e32 v103, v52
	v_mov_b32_e32 v104, v52
	v_mov_b32_e32 v105, v52
	v_mov_b32_e32 v106, v52
	v_mov_b32_e32 v107, v52
	v_mov_b32_e32 v108, v52
	v_mov_b32_e32 v109, v52
	v_mov_b32_e32 v110, v52
	v_mov_b32_e32 v111, v52
	v_mov_b32_e32 v112, v52
	v_mov_b32_e32 v113, v52
	v_mov_b32_e32 v114, v52
	v_mov_b32_e32 v115, v52
	v_mov_b32_e32 v116, v52
	v_mov_b32_e32 v117, v52
	v_mov_b32_e32 v118, v52
	v_mov_b32_e32 v119, v52
	v_mov_b32_e32 v120, v52
	v_mov_b32_e32 v121, v52
	v_mov_b32_e32 v122, v52
	v_mov_b32_e32 v123, v52
	v_mov_b32_e32 v124, v52
	v_mov_b32_e32 v125, v52
	v_mov_b32_e32 v126, v52
	v_mov_b32_e32 v127, v52
	v_mov_b32_e32 v128, v52
	v_mov_b32_e32 v129, v52
	v_mov_b32_e32 v130, v52
	v_mov_b32_e32 v131, v52
	v_mov_b32_e32 v132, v52
	v_mov_b32_e32 v133, v52
	v_mov_b32_e32 v134, v52
	v_mov_b32_e32 v135, v52
	v_mov_b32_e32 v136, v52
	v_mov_b32_e32 v137, v52
	v_mov_b32_e32 v138, v52
	v_mov_b32_e32 v139, v52
	v_mov_b32_e32 v140, v52
	v_mov_b32_e32 v141, v52
	v_mov_b32_e32 v142, v52
	v_mov_b32_e32 v143, v52
	v_mov_b32_e32 v144, v52
	v_mov_b32_e32 v145, v52
	v_mov_b32_e32 v146, v52
	v_mov_b32_e32 v147, v52
	v_mov_b32_e32 v148, v52
	v_mov_b32_e32 v149, v52
	v_mov_b32_e32 v150, v52
	v_mov_b32_e32 v151, v52
	v_mov_b32_e32 v152, v52
	v_mov_b32_e32 v153, v52
	v_mov_b32_e32 v154, v52
	v_mov_b32_e32 v155, v52
	v_mov_b32_e32 v156, v52
	v_mov_b32_e32 v157, v52
	v_mov_b32_e32 v158, v52
	v_mov_b32_e32 v159, v52
	v_mov_b32_e32 v160, v52
	v_mov_b32_e32 v161, v52
	v_mov_b32_e32 v162, v52
	v_mov_b32_e32 v163, v52
	v_mov_b32_e32 v164, v52
	v_mov_b32_e32 v165, v52
	v_mov_b32_e32 v166, v52
	v_mov_b32_e32 v167, v52
	v_mov_b32_e32 v168, v52
	v_mov_b32_e32 v169, v52
	v_mov_b32_e32 v170, v52
	v_mov_b32_e32 v171, v52
	v_mov_b32_e32 v172, v52
	v_mov_b32_e32 v173, v52
	v_mov_b32_e32 v174, v52
	v_mov_b32_e32 v175, v52
	v_mov_b32_e32 v176, v52
	v_mov_b32_e32 v177, v52
	v_mov_b32_e32 v178, v52
	v_mov_b32_e32 v179, v52
	s_waitcnt lgkmcnt(0)
	s_barrier
; template <int MI, bool SWAP, bool F8 = false>
; __device__ __forceinline__ void gemm_core(const bf16_t* __restrict__ A, int lda, const bf16_t* __restrict__ B, int ldb,
;                                           int K, char* smem, f32x4 (&acc)[MI][4]) {
;     ...
;   for (int kt = 0; kt < nk; ++kt) {
;     __syncthreads();
; #pragma unroll
;     for (int i = 0; i < MI; ++i) *(u32x4*)(smem + woff + i * 4096) = ra[i];
; #pragma unroll
;     for (int i = 0; i < 4; ++i) *(u32x4*)(smem + 32768 + woff + i * 4096) = rb[i];
;     __syncthreads();
;     if (kt + 1 < nk) {
; #pragma unroll
;       for (int i = 0; i < MI; ++i) ra[i] = *(const u32x4*)(ap + (size_t)(32 * i) * lda + (kt + 1) * 64);
; #pragma unroll
;       for (int i = 0; i < 4; ++i) rb[i] = *(const u32x4*)(bp + (size_t)(32 * i) * ldb + (kt + 1) * 64);
;     }
;     if (F8) {
;       const int c0 = (g ^ (li & 7)) << 4, c1 = ((4 + g) ^ (li & 7)) << 4;
;       i32x8 wf8[4];
; #pragma unroll
;       for (int j = 0; j < 4; ++j) {
;         const char* rp = smem + wrow + ((j & 1) * 16 + (j >> 1) * 64) * 128;
;         const u32x4 lo = *(const u32x4*)(rp + c0), hi = *(const u32x4*)(rp + c1);
;         wf8[j] = (i32x8){(int)lo.x, (int)lo.y, (int)lo.z, (int)lo.w, (int)hi.x, (int)hi.y, (int)hi.z, (int)hi.w};
;       }
; #pragma unroll
;       for (int i = 0; i < MI; ++i) {
;         const char* rp = smem + xrow + i * 2048;
;         const u32x4 lo = *(const u32x4*)(rp + c0), hi = *(const u32x4*)(rp + c1);
;         const i32x8 xf8 = {(int)lo.x, (int)lo.y, (int)lo.z, (int)lo.w, (int)hi.x, (int)hi.y, (int)hi.z, (int)hi.w};
; #pragma unroll
;         for (int j = 0; j < 4; ++j)
;           acc[i][j] = __builtin_amdgcn_mfma_scale_f32_16x16x128_f8f6f4(wf8[j], xf8, acc[i][j], 0, 0, 0, 0x77777777, 0, 0x7f7f7f7f);
;       }
	s_mov_b32 m0, s62
	s_nop 0
	global_load_lds_dwordx4 v252, s[56:57]
	s_add_u32 m0, s62, 0x1000
	s_nop 0
	global_load_lds_dwordx4 v253, s[56:57]
	s_add_u32 s56, s56, 0x10000
	s_addc_u32 s57, s57, 0
	s_add_u32 m0, s62, 0x2000
	s_nop 0
	global_load_lds_dwordx4 v252, s[56:57]
	s_add_u32 m0, s62, 0x3000
	s_nop 0
	global_load_lds_dwordx4 v253, s[56:57]
	s_add_u32 s56, s56, 0x10000
	s_addc_u32 s57, s57, 0
	s_add_u32 m0, s62, 0x4000
	s_nop 0
	global_load_lds_dwordx4 v252, s[56:57]
	s_add_u32 m0, s62, 0x5000
	s_nop 0
	global_load_lds_dwordx4 v253, s[56:57]
	s_add_u32 s56, s56, 0x10000
	s_addc_u32 s57, s57, 0
	s_add_u32 m0, s62, 0x6000
	s_nop 0
	global_load_lds_dwordx4 v252, s[56:57]
	s_add_u32 m0, s62, 0x7000
	s_nop 0
	global_load_lds_dwordx4 v253, s[56:57]
	s_sub_u32 s56, s56, 0x30000
	s_subb_u32 s57, s57, 0
	s_add_u32 m0, s62, 0x8000
	s_nop 0
	global_load_lds_dwordx4 v252, s[58:59]
	s_add_u32 m0, s62, 0x9000
	s_nop 0
	global_load_lds_dwordx4 v253, s[58:59]
	s_add_u32 s58, s58, 0x10000
	s_addc_u32 s59, s59, 0
	s_add_u32 m0, s62, 0xa000
	s_nop 0
	global_load_lds_dwordx4 v252, s[58:59]
	s_add_u32 m0, s62, 0xb000
	s_nop 0
	global_load_lds_dwordx4 v253, s[58:59]
	s_sub_u32 s58, s58, 0x10000
	s_subb_u32 s59, s59, 0
	v_add_u32_e32 v252, 0x80, v252
	v_add_u32_e32 v253, 0x80, v253
.LBB0_944:
	v_add_u32_e32 v222, v215, v218
	v_add_u32_e32 v223, v215, v219
	v_add_u32_e32 v221, v213, v218
	v_add_u32_e32 v220, v213, v219
	s_waitcnt vmcnt(0)
	s_barrier
	ds_read_b128 v[44:47], v222 offset:32768
	ds_read_b128 v[48:51], v223 offset:32768
	ds_read_b128 v[20:23], v222 offset:34816
	ds_read_b128 v[24:27], v223 offset:34816
	ds_read_b128 v[28:31], v222 offset:40960
	ds_read_b128 v[32:35], v223 offset:40960
	ds_read_b128 v[36:39], v222 offset:43008
	ds_read_b128 v[40:43], v223 offset:43008
	ds_read_b128 v[180:183], v221
	ds_read_b128 v[184:187], v220
	ds_read_b128 v[188:191], v221 offset:2048
	ds_read_b128 v[192:195], v220 offset:2048
	s_waitcnt lgkmcnt(2)
	v_mfma_scale_f32_16x16x128_f8f6f4 v[176:179], v[44:51], v[180:187], v[176:179], v239, v238 op_sel_hi:[0,0,0]
	v_mfma_scale_f32_16x16x128_f8f6f4 v[172:175], v[20:27], v[180:187], v[172:175], v239, v238 op_sel_hi:[0,0,0]
	v_mfma_scale_f32_16x16x128_f8f6f4 v[168:171], v[28:35], v[180:187], v[168:171], v239, v238 op_sel_hi:[0,0,0]
	v_mfma_scale_f32_16x16x128_f8f6f4 v[164:167], v[36:43], v[180:187], v[164:167], v239, v238 op_sel_hi:[0,0,0]
	s_waitcnt lgkmcnt(0)
	v_mfma_scale_f32_16x16x128_f8f6f4 v[160:163], v[44:51], v[188:195], v[160:163], v239, v238 op_sel_hi:[0,0,0]
	v_mfma_scale_f32_16x16x128_f8f6f4 v[156:159], v[20:27], v[188:195], v[156:159], v239, v238 op_sel_hi:[0,0,0]
	v_mfma_scale_f32_16x16x128_f8f6f4 v[152:155], v[28:35], v[188:195], v[152:155], v239, v238 op_sel_hi:[0,0,0]
	v_mfma_scale_f32_16x16x128_f8f6f4 v[148:151], v[36:43], v[188:195], v[148:151], v239, v238 op_sel_hi:[0,0,0]
	ds_read_b128 v[196:199], v221 offset:4096
	ds_read_b128 v[200:203], v220 offset:4096
	ds_read_b128 v[224:227], v221 offset:6144
	ds_read_b128 v[228:231], v220 offset:6144
	ds_read_b128 v[4:7], v221 offset:8192
	ds_read_b128 v[8:11], v220 offset:8192
	ds_read_b128 v[12:15], v221 offset:10240
	ds_read_b128 v[16:19], v220 offset:10240
	ds_read_b128 v[180:183], v221 offset:12288
	ds_read_b128 v[184:187], v220 offset:12288
	ds_read_b128 v[188:191], v221 offset:14336
	ds_read_b128 v[192:195], v220 offset:14336
	s_waitcnt lgkmcnt(0)
	s_barrier
	s_mov_b32 m0, s62
	s_nop 0
	global_load_lds_dwordx4 v252, s[56:57]
	s_add_u32 m0, s62, 0x1000
	s_nop 0
	global_load_lds_dwordx4 v253, s[56:57]
	s_add_u32 s56, s56, 0x10000
	s_addc_u32 s57, s57, 0
	s_add_u32 m0, s62, 0x2000
	s_nop 0
	global_load_lds_dwordx4 v252, s[56:57]
	s_add_u32 m0, s62, 0x3000
	s_nop 0
	global_load_lds_dwordx4 v253, s[56:57]
	s_add_u32 s56, s56, 0x10000
	s_addc_u32 s57, s57, 0
	s_add_u32 m0, s62, 0x4000
	s_nop 0
	global_load_lds_dwordx4 v252, s[56:57]
	s_add_u32 m0, s62, 0x5000
	s_nop 0
	global_load_lds_dwordx4 v253, s[56:57]
	s_add_u32 s56, s56, 0x10000
	s_addc_u32 s57, s57, 0
	s_add_u32 m0, s62, 0x6000
	s_nop 0
	global_load_lds_dwordx4 v252, s[56:57]
	s_add_u32 m0, s62, 0x7000
	s_nop 0
	global_load_lds_dwordx4 v253, s[56:57]
	s_sub_u32 s56, s56, 0x30000
	s_subb_u32 s57, s57, 0
	s_add_u32 m0, s62, 0x8000
	s_nop 0
	global_load_lds_dwordx4 v252, s[58:59]
	s_add_u32 m0, s62, 0x9000
	s_nop 0
	global_load_lds_dwordx4 v253, s[58:59]
	s_add_u32 s58, s58, 0x10000
	s_addc_u32 s59, s59, 0
	s_add_u32 m0, s62, 0xa000
	s_nop 0
	global_load_lds_dwordx4 v252, s[58:59]
	s_add_u32 m0, s62, 0xb000
	s_nop 0
	global_load_lds_dwordx4 v253, s[58:59]
	s_sub_u32 s58, s58, 0x10000
	s_subb_u32 s59, s59, 0
	v_add_u32_e32 v252, 0x80, v252
	v_add_u32_e32 v253, 0x80, v253
	v_mfma_scale_f32_16x16x128_f8f6f4 v[144:147], v[44:51], v[196:203], v[144:147], v239, v238 op_sel_hi:[0,0,0]
	v_mfma_scale_f32_16x16x128_f8f6f4 v[140:143], v[20:27], v[196:203], v[140:143], v239, v238 op_sel_hi:[0,0,0]
	v_mfma_scale_f32_16x16x128_f8f6f4 v[136:139], v[28:35], v[196:203], v[136:139], v239, v238 op_sel_hi:[0,0,0]
	v_mfma_scale_f32_16x16x128_f8f6f4 v[132:135], v[36:43], v[196:203], v[132:135], v239, v238 op_sel_hi:[0,0,0]
	v_mfma_scale_f32_16x16x128_f8f6f4 v[128:131], v[44:51], v[224:231], v[128:131], v239, v238 op_sel_hi:[0,0,0]
	v_mfma_scale_f32_16x16x128_f8f6f4 v[124:127], v[20:27], v[224:231], v[124:127], v239, v238 op_sel_hi:[0,0,0]
	v_mfma_scale_f32_16x16x128_f8f6f4 v[120:123], v[28:35], v[224:231], v[120:123], v239, v238 op_sel_hi:[0,0,0]
	v_mfma_scale_f32_16x16x128_f8f6f4 v[116:119], v[36:43], v[224:231], v[116:119], v239, v238 op_sel_hi:[0,0,0]
	v_mfma_scale_f32_16x16x128_f8f6f4 v[112:115], v[44:51], v[4:11], v[112:115], v239, v238 op_sel_hi:[0,0,0]
; template <int MI, bool SWAP, bool F8 = false>
; __device__ __forceinline__ void gemm_core(const bf16_t* __restrict__ A, int lda, const bf16_t* __restrict__ B, int ldb,
;                                           int K, char* smem, f32x4 (&acc)[MI][4]) {
;     ...
;   for (int kt = 0; kt < nk; ++kt) {
;     __syncthreads();
; #pragma unroll
;     for (int i = 0; i < MI; ++i) *(u32x4*)(smem + woff + i * 4096) = ra[i];
; #pragma unroll
;     for (int i = 0; i < 4; ++i) *(u32x4*)(smem + 32768 + woff + i * 4096) = rb[i];
;     __syncthreads();
;     if (kt + 1 < nk) {
; #pragma unroll
;       for (int i = 0; i < MI; ++i) ra[i] = *(const u32x4*)(ap + (size_t)(32 * i) * lda + (kt + 1) * 64);
; #pragma unroll
;       for (int i = 0; i < 4; ++i) rb[i] = *(const u32x4*)(bp + (size_t)(32 * i) * ldb + (kt + 1) * 64);
;     }
;     if (F8) {
;       const int c0 = (g ^ (li & 7)) << 4, c1 = ((4 + g) ^ (li & 7)) << 4;
;       i32x8 wf8[4];
; #pragma unroll
;       for (int j = 0; j < 4; ++j) {
;         const char* rp = smem + wrow + ((j & 1) * 16 + (j >> 1) * 64) * 128;
;         const u32x4 lo = *(const u32x4*)(rp + c0), hi = *(const u32x4*)(rp + c1);
;         wf8[j] = (i32x8){(int)lo.x, (int)lo.y, (int)lo.z, (int)lo.w, (int)hi.x, (int)hi.y, (int)hi.z, (int)hi.w};
;       }
; #pragma unroll
;       for (int i = 0; i < MI; ++i) {
;         const char* rp = smem + xrow + i * 2048;
;         const u32x4 lo = *(const u32x4*)(rp + c0), hi = *(const u32x4*)(rp + c1);
;         const i32x8 xf8 = {(int)lo.x, (int)lo.y, (int)lo.z, (int)lo.w, (int)hi.x, (int)hi.y, (int)hi.z, (int)hi.w};
; #pragma unroll
;         for (int j = 0; j < 4; ++j)
;           acc[i][j] = __builtin_amdgcn_mfma_scale_f32_16x16x128_f8f6f4(wf8[j], xf8, acc[i][j], 0, 0, 0, 0x77777777, 0, 0x7f7f7f7f);
;       }
	v_mfma_scale_f32_16x16x128_f8f6f4 v[108:111], v[20:27], v[4:11], v[108:111], v239, v238 op_sel_hi:[0,0,0]
	v_mfma_scale_f32_16x16x128_f8f6f4 v[104:107], v[28:35], v[4:11], v[104:107], v239, v238 op_sel_hi:[0,0,0]
	v_mfma_scale_f32_16x16x128_f8f6f4 v[100:103], v[36:43], v[4:11], v[100:103], v239, v238 op_sel_hi:[0,0,0]
	v_mfma_scale_f32_16x16x128_f8f6f4 v[96:99], v[44:51], v[12:19], v[96:99], v239, v238 op_sel_hi:[0,0,0]
	v_mfma_scale_f32_16x16x128_f8f6f4 v[92:95], v[20:27], v[12:19], v[92:95], v239, v238 op_sel_hi:[0,0,0]
	v_mfma_scale_f32_16x16x128_f8f6f4 v[88:91], v[28:35], v[12:19], v[88:91], v239, v238 op_sel_hi:[0,0,0]
	v_mfma_scale_f32_16x16x128_f8f6f4 v[84:87], v[36:43], v[12:19], v[84:87], v239, v238 op_sel_hi:[0,0,0]
	v_mfma_scale_f32_16x16x128_f8f6f4 v[80:83], v[44:51], v[180:187], v[80:83], v239, v238 op_sel_hi:[0,0,0]
	v_mfma_scale_f32_16x16x128_f8f6f4 v[76:79], v[20:27], v[180:187], v[76:79], v239, v238 op_sel_hi:[0,0,0]
	v_mfma_scale_f32_16x16x128_f8f6f4 v[72:75], v[28:35], v[180:187], v[72:75], v239, v238 op_sel_hi:[0,0,0]
	v_mfma_scale_f32_16x16x128_f8f6f4 v[68:71], v[36:43], v[180:187], v[68:71], v239, v238 op_sel_hi:[0,0,0]
	v_mfma_scale_f32_16x16x128_f8f6f4 v[64:67], v[44:51], v[188:195], v[64:67], v239, v238 op_sel_hi:[0,0,0]
	v_mfma_scale_f32_16x16x128_f8f6f4 v[60:63], v[20:27], v[188:195], v[60:63], v239, v238 op_sel_hi:[0,0,0]
	v_mfma_scale_f32_16x16x128_f8f6f4 v[56:59], v[28:35], v[188:195], v[56:59], v239, v238 op_sel_hi:[0,0,0]
	v_mfma_scale_f32_16x16x128_f8f6f4 v[52:55], v[36:43], v[188:195], v[52:55], v239, v238 op_sel_hi:[0,0,0]
	s_add_u32 s8, s8, 0x80
	s_addc_u32 s9, s9, 0
	s_cmpk_lg_i32 s8, 0x380
	s_cbranch_scc1 .LBB0_944
	s_waitcnt vmcnt(0)
	s_barrier
	v_bfe_u32 v12, v208, 4, 1
	v_mul_u32_u24_e32 v12, 24, v12
	v_mov_b32_e32 v13, 0
	ds_read_b128 v[20:23], v222 offset:32768
	ds_read_b128 v[24:27], v223 offset:32768
	ds_read_b128 v[28:31], v222 offset:34816
	ds_read_b128 v[32:35], v223 offset:34816
	ds_read_b128 v[36:39], v222 offset:40960
	ds_read_b128 v[40:43], v223 offset:40960
	ds_read_b128 v[44:47], v222 offset:43008
	ds_read_b128 v[48:51], v223 offset:43008
	ds_read_b128 v[180:183], v221
	ds_read_b128 v[184:187], v220
	s_waitcnt lgkmcnt(0)
	v_mfma_scale_f32_16x16x128_f8f6f4 v[176:179], v[20:27], v[180:187], v[176:179], v239, v238 op_sel_hi:[0,0,0]
	s_lshl_b64 s[6:7], s[6:7], 20
	s_add_u32 s6, s42, s6
	s_addc_u32 s7, s43, s7
	s_lshl_b32 s8, s19, 1
	s_add_u32 s6, s6, s8
	s_addc_u32 s7, s7, 0
	s_add_i32 s18, s18, s78
	v_mfma_scale_f32_16x16x128_f8f6f4 v[172:175], v[28:35], v[180:187], v[172:175], v239, v238 op_sel_hi:[0,0,0]
	s_add_i32 s15, s15, s71
	s_add_i32 s14, s14, s76
	s_cmpk_gt_i32 s18, 0x3ff
	v_mfma_scale_f32_16x16x128_f8f6f4 v[168:171], v[36:43], v[180:187], v[168:171], v239, v238 op_sel_hi:[0,0,0]
	v_mfma_scale_f32_16x16x128_f8f6f4 v[164:167], v[44:51], v[180:187], v[164:167], v239, v238 op_sel_hi:[0,0,0]
	ds_read_b128 v[180:183], v221 offset:2048
	ds_read_b128 v[184:187], v220 offset:2048
	s_waitcnt lgkmcnt(0)
	v_mfma_scale_f32_16x16x128_f8f6f4 v[160:163], v[20:27], v[180:187], v[160:163], v239, v238 op_sel_hi:[0,0,0]
	v_mfma_scale_f32_16x16x128_f8f6f4 v[156:159], v[28:35], v[180:187], v[156:159], v239, v238 op_sel_hi:[0,0,0]
	v_mfma_scale_f32_16x16x128_f8f6f4 v[152:155], v[36:43], v[180:187], v[152:155], v239, v238 op_sel_hi:[0,0,0]
	v_mfma_scale_f32_16x16x128_f8f6f4 v[148:151], v[44:51], v[180:187], v[148:151], v239, v238 op_sel_hi:[0,0,0]
	ds_read_b128 v[180:183], v221 offset:4096
	ds_read_b128 v[184:187], v220 offset:4096
	s_waitcnt lgkmcnt(0)
	v_mfma_scale_f32_16x16x128_f8f6f4 v[144:147], v[20:27], v[180:187], v[144:147], v239, v238 op_sel_hi:[0,0,0]
	v_mfma_scale_f32_16x16x128_f8f6f4 v[140:143], v[28:35], v[180:187], v[140:143], v239, v238 op_sel_hi:[0,0,0]
	v_mfma_scale_f32_16x16x128_f8f6f4 v[136:139], v[36:43], v[180:187], v[136:139], v239, v238 op_sel_hi:[0,0,0]
	v_mfma_scale_f32_16x16x128_f8f6f4 v[132:135], v[44:51], v[180:187], v[132:135], v239, v238 op_sel_hi:[0,0,0]
	ds_read_b128 v[180:183], v221 offset:6144
	ds_read_b128 v[184:187], v220 offset:6144
	s_waitcnt lgkmcnt(0)
	v_mfma_scale_f32_16x16x128_f8f6f4 v[128:131], v[20:27], v[180:187], v[128:131], v239, v238 op_sel_hi:[0,0,0]
	v_mfma_scale_f32_16x16x128_f8f6f4 v[124:127], v[28:35], v[180:187], v[124:127], v239, v238 op_sel_hi:[0,0,0]
	v_mfma_scale_f32_16x16x128_f8f6f4 v[120:123], v[36:43], v[180:187], v[120:123], v239, v238 op_sel_hi:[0,0,0]
	v_mfma_scale_f32_16x16x128_f8f6f4 v[116:119], v[44:51], v[180:187], v[116:119], v239, v238 op_sel_hi:[0,0,0]
	ds_read_b128 v[180:183], v221 offset:8192
	ds_read_b128 v[184:187], v220 offset:8192
	s_waitcnt lgkmcnt(0)
	v_mfma_scale_f32_16x16x128_f8f6f4 v[112:115], v[20:27], v[180:187], v[112:115], v239, v238 op_sel_hi:[0,0,0]
	v_mfma_scale_f32_16x16x128_f8f6f4 v[108:111], v[28:35], v[180:187], v[108:111], v239, v238 op_sel_hi:[0,0,0]
	v_mfma_scale_f32_16x16x128_f8f6f4 v[104:107], v[36:43], v[180:187], v[104:107], v239, v238 op_sel_hi:[0,0,0]
	v_mfma_scale_f32_16x16x128_f8f6f4 v[100:103], v[44:51], v[180:187], v[100:103], v239, v238 op_sel_hi:[0,0,0]
	ds_read_b128 v[180:183], v221 offset:10240
	ds_read_b128 v[184:187], v220 offset:10240
	s_waitcnt lgkmcnt(0)
	v_mfma_scale_f32_16x16x128_f8f6f4 v[96:99], v[20:27], v[180:187], v[96:99], v239, v238 op_sel_hi:[0,0,0]
	v_mfma_scale_f32_16x16x128_f8f6f4 v[92:95], v[28:35], v[180:187], v[92:95], v239, v238 op_sel_hi:[0,0,0]
	v_mfma_scale_f32_16x16x128_f8f6f4 v[88:91], v[36:43], v[180:187], v[88:91], v239, v238 op_sel_hi:[0,0,0]
	v_mfma_scale_f32_16x16x128_f8f6f4 v[84:87], v[44:51], v[180:187], v[84:87], v239, v238 op_sel_hi:[0,0,0]
	ds_read_b128 v[180:183], v221 offset:12288
	ds_read_b128 v[184:187], v220 offset:12288
	s_waitcnt lgkmcnt(0)
; template <int MI, bool SWAP, bool F8 = false>
; __device__ __forceinline__ void gemm_core(const bf16_t* __restrict__ A, int lda, const bf16_t* __restrict__ B, int ldb,
;                                           int K, char* smem, f32x4 (&acc)[MI][4]) {
;     ...
;       for (int i = 0; i < MI; ++i) {
;         const char* rp = smem + xrow + i * 2048;
;         const u32x4 lo = *(const u32x4*)(rp + c0), hi = *(const u32x4*)(rp + c1);
;         const i32x8 xf8 = {(int)lo.x, (int)lo.y, (int)lo.z, (int)lo.w, (int)hi.x, (int)hi.y, (int)hi.z, (int)hi.w};
; #pragma unroll
;         for (int j = 0; j < 4; ++j)
;           acc[i][j] = __builtin_amdgcn_mfma_scale_f32_16x16x128_f8f6f4(wf8[j], xf8, acc[i][j], 0, 0, 0, 0x77777777, 0, 0x7f7f7f7f);
;       }
; template <int MI, bool F8 = false>
; __device__ void gemm_tile_bf16(const bf16_t* A, int lda, const bf16_t* B, int ldb, int K, bf16_t* C, int ldc, char* smem) {
;     ...
; #pragma unroll
;   for (int i = 0; i < MI; ++i)
; #pragma unroll
;     for (int j = 0; j < 4; ++j) {
;       u32x2 v;
;       v.x = pk_bf16(acc[i][j][0], acc[i][j][1]);
;       v.y = pk_bf16(acc[i][j][2], acc[i][j][3]);
;       *(u32x2*)(C + (size_t)MROW(i) * ldc + NCOL(j)) = v;
;     }
	v_mfma_scale_f32_16x16x128_f8f6f4 v[80:83], v[20:27], v[180:187], v[80:83], v239, v238 op_sel_hi:[0,0,0]
	v_mfma_scale_f32_16x16x128_f8f6f4 v[76:79], v[28:35], v[180:187], v[76:79], v239, v238 op_sel_hi:[0,0,0]
	v_mfma_scale_f32_16x16x128_f8f6f4 v[72:75], v[36:43], v[180:187], v[72:75], v239, v238 op_sel_hi:[0,0,0]
	v_mfma_scale_f32_16x16x128_f8f6f4 v[68:71], v[44:51], v[180:187], v[68:71], v239, v238 op_sel_hi:[0,0,0]
	ds_read_b128 v[180:183], v221 offset:14336
	ds_read_b128 v[184:187], v220 offset:14336
	s_waitcnt lgkmcnt(0)
	v_mfma_scale_f32_16x16x128_f8f6f4 v[64:67], v[20:27], v[180:187], v[64:67], v239, v238 op_sel_hi:[0,0,0]
	v_mfma_scale_f32_16x16x128_f8f6f4 v[24:27], v[36:43], v[180:187], v[56:59], v239, v238 op_sel_hi:[0,0,0]
	v_mov_b32_e32 v36, v208
	s_nop 0
	v_lshrrev_b32_e32 v0, 1, v36
	v_and_b32_e32 v2, 0xffffff8f, v36
	v_and_b32_e32 v0, 32, v0
	v_lshrrev_b32_e32 v3, 2, v36
	v_and_or_b32 v0, v3, 12, v0
	v_ashrrev_i32_e32 v3, 31, v2
	v_mfma_scale_f32_16x16x128_f8f6f4 v[28:31], v[28:35], v[180:187], v[60:63], v239, v238 op_sel_hi:[0,0,0]
	v_lshlrev_b64 v[32:33], 12, v[2:3]
	v_lshl_add_u64 v[32:33], s[6:7], 0, v[32:33]
	v_lshlrev_b32_e32 v0, 1, v0
	v_cvt_pk_bf16_f32 v4, v176, v177
	v_cvt_pk_bf16_f32 v5, v178, v179
	v_lshl_add_u64 v[32:33], v[32:33], 0, v[0:1]
	v_cvt_pk_bf16_f32 v6, v172, v173
	v_cvt_pk_bf16_f32 v7, v174, v175
	s_nop 1
	v_permlane16_swap_b32_e32 v4, v6
	v_permlane16_swap_b32_e32 v5, v7
	v_lshl_add_u64 v[14:15], v[32:33], 0, v[12:13]
	global_store_dwordx4 v[14:15], v[4:7], off
	v_cvt_pk_bf16_f32 v8, v168, v169
	v_cvt_pk_bf16_f32 v9, v170, v171
	v_cvt_pk_bf16_f32 v10, v164, v165
	v_cvt_pk_bf16_f32 v11, v166, v167
	s_nop 1
	v_permlane16_swap_b32_e32 v8, v10
	v_permlane16_swap_b32_e32 v9, v11
	v_lshl_add_u64 v[14:15], v[32:33], 0, v[12:13]
	global_store_dwordx4 v[14:15], v[8:11], off offset:128
	v_or_b32_e32 v32, 16, v2
	v_ashrrev_i32_e32 v33, 31, v32
	v_lshlrev_b64 v[32:33], 12, v[32:33]
	v_lshl_add_u64 v[32:33], s[6:7], 0, v[32:33]
	v_cvt_pk_bf16_f32 v4, v160, v161
	v_cvt_pk_bf16_f32 v5, v162, v163
	v_lshl_add_u64 v[32:33], v[32:33], 0, v[0:1]
	v_cvt_pk_bf16_f32 v6, v156, v157
	v_cvt_pk_bf16_f32 v7, v158, v159
	s_nop 1
	v_permlane16_swap_b32_e32 v4, v6
	v_permlane16_swap_b32_e32 v5, v7
	v_lshl_add_u64 v[14:15], v[32:33], 0, v[12:13]
	global_store_dwordx4 v[14:15], v[4:7], off
	v_cvt_pk_bf16_f32 v8, v152, v153
	v_cvt_pk_bf16_f32 v9, v154, v155
	v_cvt_pk_bf16_f32 v10, v148, v149
	v_cvt_pk_bf16_f32 v11, v150, v151
	s_nop 1
	v_permlane16_swap_b32_e32 v8, v10
	v_permlane16_swap_b32_e32 v9, v11
	v_lshl_add_u64 v[14:15], v[32:33], 0, v[12:13]
	global_store_dwordx4 v[14:15], v[8:11], off offset:128
	v_or_b32_e32 v32, 32, v2
	v_ashrrev_i32_e32 v33, 31, v32
	v_lshlrev_b64 v[32:33], 12, v[32:33]
	v_lshl_add_u64 v[32:33], s[6:7], 0, v[32:33]
	v_cvt_pk_bf16_f32 v4, v144, v145
	v_cvt_pk_bf16_f32 v5, v146, v147
	v_lshl_add_u64 v[32:33], v[32:33], 0, v[0:1]
	v_cvt_pk_bf16_f32 v6, v140, v141
	v_cvt_pk_bf16_f32 v7, v142, v143
	s_nop 1
	v_permlane16_swap_b32_e32 v4, v6
	v_permlane16_swap_b32_e32 v5, v7
	v_lshl_add_u64 v[14:15], v[32:33], 0, v[12:13]
	global_store_dwordx4 v[14:15], v[4:7], off
	v_cvt_pk_bf16_f32 v8, v136, v137
	v_cvt_pk_bf16_f32 v9, v138, v139
	v_cvt_pk_bf16_f32 v10, v132, v133
	v_cvt_pk_bf16_f32 v11, v134, v135
	s_nop 1
	v_permlane16_swap_b32_e32 v8, v10
	v_permlane16_swap_b32_e32 v9, v11
	v_lshl_add_u64 v[14:15], v[32:33], 0, v[12:13]
	global_store_dwordx4 v[14:15], v[8:11], off offset:128
	v_or_b32_e32 v32, 48, v2
	v_ashrrev_i32_e32 v33, 31, v32
	v_lshlrev_b64 v[32:33], 12, v[32:33]
	v_lshl_add_u64 v[32:33], s[6:7], 0, v[32:33]
	v_cvt_pk_bf16_f32 v4, v128, v129
	v_cvt_pk_bf16_f32 v5, v130, v131
	v_lshl_add_u64 v[32:33], v[32:33], 0, v[0:1]
	v_cvt_pk_bf16_f32 v6, v124, v125
	v_cvt_pk_bf16_f32 v7, v126, v127
	s_nop 1
	v_permlane16_swap_b32_e32 v4, v6
	v_permlane16_swap_b32_e32 v5, v7
; template <int MI, bool F8 = false>
; __device__ void gemm_tile_bf16(const bf16_t* A, int lda, const bf16_t* B, int ldb, int K, bf16_t* C, int ldc, char* smem) {
;     ...
; #pragma unroll
;   for (int i = 0; i < MI; ++i)
; #pragma unroll
;     for (int j = 0; j < 4; ++j) {
;       u32x2 v;
;       v.x = pk_bf16(acc[i][j][0], acc[i][j][1]);
;       v.y = pk_bf16(acc[i][j][2], acc[i][j][3]);
;       *(u32x2*)(C + (size_t)MROW(i) * ldc + NCOL(j)) = v;
;     }
	v_lshl_add_u64 v[14:15], v[32:33], 0, v[12:13]
	global_store_dwordx4 v[14:15], v[4:7], off
	v_cvt_pk_bf16_f32 v8, v120, v121
	v_cvt_pk_bf16_f32 v9, v122, v123
	v_cvt_pk_bf16_f32 v10, v116, v117
	v_cvt_pk_bf16_f32 v11, v118, v119
	s_nop 1
	v_permlane16_swap_b32_e32 v8, v10
	v_permlane16_swap_b32_e32 v9, v11
	v_lshl_add_u64 v[14:15], v[32:33], 0, v[12:13]
	global_store_dwordx4 v[14:15], v[8:11], off offset:128
	v_or_b32_e32 v32, 64, v2
	v_ashrrev_i32_e32 v33, 31, v32
	v_lshlrev_b64 v[32:33], 12, v[32:33]
	v_lshl_add_u64 v[32:33], s[6:7], 0, v[32:33]
	v_cvt_pk_bf16_f32 v4, v112, v113
	v_cvt_pk_bf16_f32 v5, v114, v115
	v_lshl_add_u64 v[32:33], v[32:33], 0, v[0:1]
	v_cvt_pk_bf16_f32 v6, v108, v109
	v_cvt_pk_bf16_f32 v7, v110, v111
	s_nop 1
	v_permlane16_swap_b32_e32 v4, v6
	v_permlane16_swap_b32_e32 v5, v7
	v_lshl_add_u64 v[14:15], v[32:33], 0, v[12:13]
	global_store_dwordx4 v[14:15], v[4:7], off
	v_cvt_pk_bf16_f32 v8, v104, v105
	v_cvt_pk_bf16_f32 v9, v106, v107
	v_cvt_pk_bf16_f32 v10, v100, v101
	v_cvt_pk_bf16_f32 v11, v102, v103
	s_nop 1
	v_permlane16_swap_b32_e32 v8, v10
	v_permlane16_swap_b32_e32 v9, v11
	v_lshl_add_u64 v[14:15], v[32:33], 0, v[12:13]
	global_store_dwordx4 v[14:15], v[8:11], off offset:128
	v_or_b32_e32 v32, 0x50, v2
	v_ashrrev_i32_e32 v33, 31, v32
	v_lshlrev_b64 v[32:33], 12, v[32:33]
	v_lshl_add_u64 v[32:33], s[6:7], 0, v[32:33]
	v_cvt_pk_bf16_f32 v4, v96, v97
	v_cvt_pk_bf16_f32 v5, v98, v99
	v_lshl_add_u64 v[32:33], v[32:33], 0, v[0:1]
	v_or_b32_e32 v2, 0x60, v2
	v_cvt_pk_bf16_f32 v6, v92, v93
	v_cvt_pk_bf16_f32 v7, v94, v95
	v_ashrrev_i32_e32 v3, 31, v2
	s_nop 1
	v_permlane16_swap_b32_e32 v4, v6
	v_permlane16_swap_b32_e32 v5, v7
	v_lshl_add_u64 v[14:15], v[32:33], 0, v[12:13]
	global_store_dwordx4 v[14:15], v[4:7], off
	v_cvt_pk_bf16_f32 v8, v88, v89
	v_cvt_pk_bf16_f32 v9, v90, v91
	v_lshlrev_b64 v[2:3], 12, v[2:3]
	v_cvt_pk_bf16_f32 v10, v84, v85
	v_cvt_pk_bf16_f32 v11, v86, v87
	v_lshl_add_u64 v[2:3], s[6:7], 0, v[2:3]
	v_mfma_scale_f32_16x16x128_f8f6f4 v[20:23], v[44:51], v[180:187], v[52:55], v239, v238 op_sel_hi:[0,0,0]
	s_nop 1
	v_permlane16_swap_b32_e32 v8, v10
	v_permlane16_swap_b32_e32 v9, v11
	v_lshl_add_u64 v[14:15], v[32:33], 0, v[12:13]
	global_store_dwordx4 v[14:15], v[8:11], off offset:128
	v_cvt_pk_bf16_f32 v4, v80, v81
	v_cvt_pk_bf16_f32 v5, v82, v83
	v_lshl_add_u64 v[2:3], v[2:3], 0, v[0:1]
	v_cvt_pk_bf16_f32 v6, v76, v77
	v_cvt_pk_bf16_f32 v7, v78, v79
	s_nop 1
	v_permlane16_swap_b32_e32 v4, v6
	v_permlane16_swap_b32_e32 v5, v7
	v_lshl_add_u64 v[14:15], v[2:3], 0, v[12:13]
	global_store_dwordx4 v[14:15], v[4:7], off
	v_cvt_pk_bf16_f32 v8, v72, v73
	v_cvt_pk_bf16_f32 v9, v74, v75
	v_cvt_pk_bf16_f32 v10, v68, v69
	v_cvt_pk_bf16_f32 v11, v70, v71
	s_nop 1
	v_permlane16_swap_b32_e32 v8, v10
	v_permlane16_swap_b32_e32 v9, v11
	v_lshl_add_u64 v[14:15], v[2:3], 0, v[12:13]
	global_store_dwordx4 v[14:15], v[8:11], off offset:128
	v_or_b32_e32 v2, 0x70, v36
	v_ashrrev_i32_e32 v3, 31, v2
	v_lshlrev_b64 v[2:3], 12, v[2:3]
	v_lshl_add_u64 v[2:3], s[6:7], 0, v[2:3]
	v_cvt_pk_bf16_f32 v32, v64, v65
	v_cvt_pk_bf16_f32 v33, v66, v67
	v_lshl_add_u64 v[2:3], v[2:3], 0, v[0:1]
	v_cvt_pk_bf16_f32 v28, v28, v29
	v_cvt_pk_bf16_f32 v29, v30, v31
	v_cvt_pk_bf16_f32 v24, v24, v25
	v_cvt_pk_bf16_f32 v25, v26, v27
	v_cvt_pk_bf16_f32 v20, v20, v21
	v_cvt_pk_bf16_f32 v21, v22, v23
	v_mov_b64_e32 v[4:5], v[32:33]
	v_mov_b64_e32 v[6:7], v[28:29]
	s_nop 1
	v_permlane16_swap_b32_e32 v4, v6
	v_permlane16_swap_b32_e32 v5, v7
	v_lshl_add_u64 v[14:15], v[2:3], 0, v[12:13]
	global_store_dwordx4 v[14:15], v[4:7], off
	v_mov_b64_e32 v[8:9], v[24:25]
	v_mov_b64_e32 v[10:11], v[20:21]
	s_nop 1
	v_permlane16_swap_b32_e32 v8, v10
	v_permlane16_swap_b32_e32 v9, v11
	v_lshl_add_u64 v[14:15], v[2:3], 0, v[12:13]
	global_store_dwordx4 v[14:15], v[8:11], off offset:128
	s_cbranch_scc0 .LBB0_943
